# v16 with pool/conv units rebalanced (0,6): CUs 0-127 skip pool/conv (they run a context-attention unit)
# baseline (speedup 1.0000x reference)
.LBB0_242:
	s_or_b64 exec, exec, s[4:5]
	s_cmpk_lg_i32 s16, 0x100
	s_cselect_b64 s[0:1], -1, 0
	s_cmpk_eq_i32 s16, 0x100
	v_writelane_b32 v254, s0, 0
	s_movk_i32 s4, 0x800
	s_mul_i32 s70, s17, s16
	v_writelane_b32 v254, s1, 1
	s_cselect_b64 s[0:1], -1, 0
	v_writelane_b32 v254, s0, 2
	s_mul_i32 s70, s70, s3
	s_mov_b32 s47, 0
	v_writelane_b32 v254, s1, 3
	s_and_b64 s[0:1], s[0:1], exec
	s_cselect_b32 s22, s4, 0x840
	s_cselect_b32 s24, s16, 0x180
	s_cmp_lt_i32 s2, s22
	s_cselect_b64 s[0:1], -1, 0
	v_writelane_b32 v254, s0, 4
	s_ashr_i32 s17, s2, 31
	s_and_b32 s21, s2, 15
	v_writelane_b32 v254, s1, 5
	s_lshr_b32 s0, s17, 29
	s_add_i32 s0, s2, s0
	s_ashr_i32 s7, s0, 3
	s_and_b32 s0, s0, -8
	s_or_b32 s4, s21, 0xb0
	s_ashr_i32 s6, s2, 4
	s_sub_i32 s12, s2, s0
	s_add_i32 s0, s6, 14
	s_lshl_b32 s1, s4, 18
	v_writelane_b32 v254, s1, 6
	s_ashr_i32 s1, s0, 31
	s_lshl_b64 s[8:9], s[0:1], 19
	s_lshr_b32 s86, s22, 3
	v_writelane_b32 v254, s8, 7
	s_lshl_b32 s1, s4, 7
	s_lshl_b32 s4, s0, 8
	s_or_b32 s87, s86, 1
	s_ashr_i32 s39, s16, 31
	v_writelane_b32 v254, s9, 8
	s_ashr_i32 s5, s4, 31
	s_lshl_b32 s0, s0, 7
	v_writelane_b32 v254, s1, 9
	s_cmpk_lt_i32 s2, 0x240
	v_writelane_b32 v254, s0, 10
	s_cselect_b64 s[0:1], -1, 0
	v_writelane_b32 v254, s0, 11
	s_cmpk_lt_i32 s2, 0x180
	s_mov_b32 s19, s47
	v_writelane_b32 v254, s1, 12
	s_cselect_b64 s[0:1], -1, 0
	v_writelane_b32 v254, s0, 13
	s_cmpk_lt_i32 s2, 0x300
	s_mov_b32 s23, s47
	v_writelane_b32 v254, s1, 14
	s_cselect_b64 s[0:1], -1, 0
	v_writelane_b32 v254, s0, 15
	s_mov_b32 s8, s2
	s_mov_b32 s25, s47
	v_writelane_b32 v254, s1, 16
	s_mul_i32 s0, s2, 6
	s_add_i32 s9, s0, 0xfffffd00
	s_cmpk_lt_i32 s2, 0x80
	s_cselect_b64 s[0:1], -1, 0
	v_writelane_b32 v254, s0, 17
	s_movk_i32 s71, 0x1600
	s_mov_b64 s[62:63], 0x5000000
	v_writelane_b32 v254, s1, 18
	s_and_b64 s[0:1], s[0:1], exec
	s_cselect_b32 s67, s8, s9
	s_cselect_b32 s81, 1, 6
	s_lshl_b32 s1, s67, 5
	s_and_b32 s8, s1, 0xffffff00
	s_and_b32 s10, s1, 0x7ffff000
	s_add_i32 s9, s8, 0x100
	s_add_i32 s11, s10, 0x1000
	s_cmpk_lt_i32 s67, 0x100
	s_cselect_b32 s0, s9, s11
	v_writelane_b32 v254, s0, 19
	s_cselect_b32 s0, s8, s10
	v_writelane_b32 v254, s0, 20
	s_add_i32 s0, s1, -15
	v_writelane_b32 v254, s0, 21
	s_add_i32 s0, s1, -8
	s_cmp_lt_i32 s2, s24
	v_writelane_b32 v254, s0, 22
	s_cselect_b64 s[0:1], -1, 0
	v_writelane_b32 v254, s0, 23
	s_mov_b32 s11, s47
	s_waitcnt lgkmcnt(0)
	v_mov_b32_e32 v0, 0
	v_writelane_b32 v254, s1, 24
	s_lshr_b32 s0, s24, 3
	s_cmpk_lt_i32 s2, 0x100
	s_cselect_b64 s[8:9], -1, 0
	v_writelane_b32 v254, s8, 25
	s_and_b32 s1, s33, 56
	s_mov_b64 s[76:77], 0x80
	v_writelane_b32 v254, s9, 26
	s_bfe_u32 s8, s2, 0x30003
	s_or_b32 s1, s8, s1
	s_or_b32 s8, s1, 0x80
	s_ashr_i32 s9, s2, 6
	v_writelane_b32 v254, s8, 27
	v_writelane_b32 v254, s9, 28
	s_lshl_b32 s9, s9, 8
	s_lshl_b32 s8, s8, 7
	v_writelane_b32 v254, s9, 29
	v_writelane_b32 v254, s8, 30
	s_addk_i32 s8, 0xe000
	s_lshr_b32 s8, s8, 12
	s_add_i32 s8, s8, 1
	s_lshl_b32 s10, s8, 10
	s_cmp_lt_i32 s12, 0
	s_cselect_b32 s3, s87, s86
	s_mul_i32 s46, s8, 0x2400
	s_mul_i32 s3, s3, s12
	s_movk_i32 s8, 0x49
	s_cselect_b32 s13, s8, 0x48
	s_add_i32 s3, s3, s7
	s_mul_hi_i32 s8, s3, 0x2e8ba2e9
	s_lshr_b32 s9, s8, 31
	s_ashr_i32 s8, s8, 5
	s_add_i32 s8, s8, s9
	s_mul_i32 s9, s8, 0xb0
	v_writelane_b32 v254, s10, 31
	s_sub_i32 s3, s3, s9
	v_mov_b32_e32 v229, 0x358637bd
	v_writelane_b32 v254, s11, 32
	s_lshl_b32 s10, s8, 3
	s_bfe_u32 s8, s3, 0x3001c
	s_add_i32 s9, s3, s8
	s_sext_i32_i16 s11, s9
	s_and_b32 s9, s9, 0xfff8
	s_sub_i32 s3, s3, s9
	s_sext_i32_i16 s3, s3
	s_add_i32 s14, s10, s3
	s_ashr_i32 s15, s14, 31
	s_lshr_b32 s8, s11, 3
	s_ashr_i32 s20, s11, 3
	s_lshl_b64 s[10:11], s[14:15], 19
	v_writelane_b32 v254, s10, 33
	s_bfe_i64 s[8:9], s[8:9], 0x100000
	s_lshl_b64 s[8:9], s[8:9], 19
	v_writelane_b32 v254, s11, 34
	s_lshl_b32 s10, s14, 8
	s_add_i32 s3, s10, 0xffffe000
	s_lshr_b32 s3, s3, 12
	s_mulk_i32 s3, 0x1600
	s_ashr_i32 s11, s10, 31
	s_addk_i32 s3, 0x1600
	v_writelane_b32 v254, s8, 35
	s_cmp_gt_i32 s14, 31
	s_cselect_b32 s18, s3, 0
	v_writelane_b32 v254, s9, 36
	s_mov_b32 s8, s14
	s_mul_i32 s3, s12, s13
	v_writelane_b32 v254, s8, 37
	s_add_i32 s3, s3, s7
	s_lshl_b32 s26, s20, 8
	v_writelane_b32 v254, s9, 38
	s_mul_hi_i32 s8, s3, 0x2aaaaaab
	s_lshr_b32 s9, s8, 31
	s_ashr_i32 s8, s8, 3
	s_add_i32 s8, s8, s9
	s_lshl_b32 s9, s8, 3
	s_mul_i32 s8, s8, 48
	s_sub_i32 s3, s3, s8
	s_bfe_i32 s8, s3, 0x80000
	s_bfe_u32 s8, s8, 0x3000c
	s_add_i32 s13, s3, s8
	s_bfe_i32 s8, s13, 0x80000
	s_and_b32 s13, s13, 0xf8
	s_sub_i32 s3, s3, s13
	s_sext_i32_i8 s3, s3
	s_add_i32 s28, s9, s3
	s_lshr_b32 s3, s12, 31
	s_or_b32 s3, s0, s3
	s_mul_i32 s3, s3, s12
	s_add_i32 s3, s3, s7
	s_ashr_i32 s7, s3, 31
	s_lshr_b32 s7, s7, 27
	s_add_i32 s7, s3, s7
	s_ashr_i32 s9, s7, 5
	s_and_b32 s7, s7, 0xffe0
	s_sub_i32 s3, s3, s7
	s_bfe_i32 s7, s3, 0x80000
	s_bfe_u32 s7, s7, 0x3000c
	s_add_i32 s7, s3, s7
	s_bfe_i32 s12, s7, 0x80000
	s_and_b32 s7, s7, 0xf8
	s_sub_i32 s3, s3, s7
	v_writelane_b32 v254, s20, 39
	s_lshl_b32 s9, s9, 3
	s_sext_i32_i8 s3, s3
	v_writelane_b32 v254, s0, 40
	s_sext_i32_i16 s12, s12
	s_add_i32 s0, s9, s3
	s_sext_i32_i16 s14, s8
	v_writelane_b32 v254, s0, 41
	s_ashr_i32 s0, s12, 3
	s_ashr_i32 s29, s28, 31
	s_lshr_b32 s8, s14, 3
	s_lshr_b32 s20, s12, 3
	v_writelane_b32 v254, s0, 42
	s_lshl_b64 s[12:13], s[28:29], 19
	v_writelane_b32 v254, s12, 43
	s_bfe_i64 s[8:9], s[8:9], 0x100000
	s_lshl_b64 s[8:9], s[8:9], 19
	v_writelane_b32 v254, s13, 44
	v_writelane_b32 v254, s8, 45
	s_mov_b32 s0, s28
	s_ashr_i32 s27, s26, 31
	v_writelane_b32 v254, s9, 46
	s_lshl_b32 s8, s28, 8
	s_add_i32 s3, s8, 0xffffe000
	s_lshr_b32 s3, s3, 12
	s_mulk_i32 s3, 0x600
	s_ashr_i32 s14, s14, 3
	s_ashr_i32 s9, s8, 31
	s_addk_i32 s3, 0x600
	v_writelane_b32 v254, s0, 47
	s_cmp_gt_i32 s28, 31
	s_cselect_b32 s12, s3, 0
	v_writelane_b32 v254, s1, 48
	v_writelane_b32 v254, s14, 49
	s_bfe_i64 s[28:29], s[20:21], 0x100000
	v_writelane_b32 v254, s28, 50
	s_lshl_b32 s14, s14, 8
	s_lshl_b32 s0, s21, 18
	v_writelane_b32 v254, s29, 51
	s_ashr_i32 s7, s6, 31
	s_ashr_i32 s15, s14, 31
	v_writelane_b32 v254, s0, 52
	s_or_b32 s0, s0, 0x7c00080
	s_lshl_b64 s[6:7], s[6:7], 19
	v_writelane_b32 v254, s0, 53
	s_add_u32 s0, s6, 0xb00100
	v_writelane_b32 v254, s0, 54
	s_addc_u32 s0, s7, 0
	s_lshl_b32 s1, s1, 8
	v_writelane_b32 v254, s0, 55
	s_or_b32 s0, s1, 0x8000
	v_writelane_b32 v254, s0, 56
	s_lshl_b64 s[0:1], s[10:11], 2
	v_writelane_b32 v254, s0, 57
	s_mov_b32 s13, s47
	s_add_i32 s88, 0, 0x200c8
	v_writelane_b32 v254, s1, 58
	s_lshl_b64 s[0:1], s[18:19], 2
	v_writelane_b32 v254, s0, 59
	s_add_i32 s89, 0, 0x200cc
	s_mov_b32 s92, 0x800000
	v_writelane_b32 v254, s1, 60
	s_lshl_b64 s[0:1], s[26:27], 2
	v_writelane_b32 v254, s0, 61
	s_mov_b64 s[78:79], 0x8000000
	s_add_i32 s93, 0, 0x200c0
	v_writelane_b32 v254, s1, 62
	s_lshl_b64 s[0:1], s[4:5], 2
	v_writelane_b32 v254, s0, 63
	s_add_i32 s94, 0, 0x200c4
	s_add_i32 s95, 0, 0x200a8
	v_writelane_b32 v255, s1, 0
	s_lshl_b64 s[0:1], s[8:9], 2
	v_writelane_b32 v255, s0, 1
	s_add_i32 s96, 0, 0x200ac
	s_add_i32 s97, 0, 0x200b0
	v_writelane_b32 v255, s1, 2
	s_lshl_b64 s[0:1], s[12:13], 2
	v_writelane_b32 v255, s0, 3
	s_add_i32 s28, 0, 0x200b4
	v_mov_b32_e32 v252, 0x1000
	v_writelane_b32 v255, s1, 4
	s_lshl_b64 s[0:1], s[14:15], 2
	v_writelane_b32 v255, s0, 5
	v_mov_b32_e32 v253, 0x2000
	v_mov_b32_e32 v235, 1
	v_writelane_b32 v255, s1, 6
	s_add_i32 s0, 0, 0x20100
	v_writelane_b32 v255, s0, 7
	s_add_i32 s0, 0, 0x20104
	v_writelane_b32 v255, s0, 8
	s_add_i32 s0, 0, 0x10400
	v_writelane_b32 v255, s0, 9
	s_add_i32 s0, 0, 0x10800
	v_writelane_b32 v255, s0, 10
	s_add_i32 s0, 0, 0x10c00
	v_writelane_b32 v255, s0, 11
	s_add_i32 s0, 0, 0x11000
	v_writelane_b32 v255, s0, 12
	s_add_i32 s0, 0, 0x11400
	v_writelane_b32 v255, s0, 13
	s_add_i32 s0, 0, 0x11800
	v_writelane_b32 v255, s0, 14
	s_add_i32 s0, 0, 0x20088
	v_writelane_b32 v255, s0, 15
	s_add_i32 s0, 0, 0x2008c
	v_writelane_b32 v255, s0, 16
	s_add_i32 s0, 0, 0x20090
	v_writelane_b32 v255, s0, 17
	s_add_i32 s0, 0, 0x20094
	v_writelane_b32 v255, s0, 18
	s_add_i32 s0, 0, 0x20098
	v_writelane_b32 v255, s0, 19
	s_add_i32 s0, 0, 0x2009c
	v_writelane_b32 v255, s0, 20
	s_lshl_b64 s[0:1], s[46:47], 2
	v_writelane_b32 v255, s0, 21
	s_add_i32 s29, 0, 0x200b8
	s_add_i32 s90, 0, 0x200bc
	v_writelane_b32 v255, s1, 22
	v_writelane_b32 v255, s72, 23
	s_movk_i32 s91, 0xfefe
	s_mov_b32 s33, 0x41000000
	v_writelane_b32 v255, s73, 24
	v_writelane_b32 v255, s86, 25
	v_writelane_b32 v255, s87, 26
	s_mov_b32 s80, 0x3b800000
	s_mov_b32 s64, 0x358637bd
	s_mov_b64 s[48:49], 0x3a2000
	s_mov_b64 s[54:55], 0x10480000
	s_mov_b64 s[18:19], 0x104c0000
	v_mov_b32_e32 v234, 0xf149f2ca
	v_mov_b32_e32 v236, 63
	s_mov_b32 s74, 0
	v_writelane_b32 v255, s67, 27
	s_barrier
	s_branch .LBB0_246

.LBB0_546:
	s_andn2_b64 vcc, exec, s[4:5]
	s_cbranch_vccnz .LBB0_605
	s_cmpk_lt_u32 s2, 0x80
	s_cbranch_scc1 .LBB0_605
	v_mov_b32_e32 v1, s88
	ds_read_b32 v1, v1
	v_mov_b32_e32 v2, s89
	ds_read_b32 v2, v2
	v_readlane_b32 s0, v255, 15
	s_waitcnt lgkmcnt(1)
	v_readfirstlane_b32 s14, v1
	v_and_b32_e32 v22, 31, v48
	v_mov_b32_e32 v1, s0
	v_readlane_b32 s0, v255, 16
	s_waitcnt lgkmcnt(0)
	v_readfirstlane_b32 s15, v2
	ds_read_b32 v1, v1
	v_mov_b32_e32 v2, s0
	v_readlane_b32 s0, v255, 17
	ds_read_b32 v2, v2
	v_lshlrev_b32_e32 v36, 4, v22
	v_mov_b32_e32 v3, s0
	ds_read_b32 v3, v3
	v_readlane_b32 s0, v255, 18
	v_mov_b32_e32 v37, v0
	s_waitcnt lgkmcnt(1)
	v_readfirstlane_b32 s26, v2
	v_mov_b32_e32 v4, s0
	v_readlane_b32 s0, v255, 19
	ds_read_b32 v4, v4
	s_waitcnt lgkmcnt(1)
	v_readfirstlane_b32 s21, v3
	v_mov_b32_e32 v5, s0
	v_readlane_b32 s0, v255, 20
	ds_read_b32 v5, v5
	v_ashrrev_i32_e32 v130, 5, v48
	v_mov_b32_e32 v6, s0
	ds_read_b32 v6, v6
	v_lshl_add_u64 v[2:3], s[14:15], 0, v[36:37]
	s_mov_b64 s[4:5], 0x8c00000
	v_readlane_b32 s0, v254, 21
	v_lshl_add_u64 v[40:41], v[2:3], 0, s[4:5]
	v_cmp_gt_i32_e64 s[10:11], 62, v130
	v_add_u32_e32 v2, s0, v130
	v_readlane_b32 s0, v254, 20
	v_mov_b32_e32 v8, v0
	v_mov_b32_e32 v9, v0
	v_cmp_le_i32_e32 vcc, s0, v2
	v_readlane_b32 s0, v254, 19
	s_waitcnt lgkmcnt(2)
	v_readfirstlane_b32 s3, v4
	s_waitcnt lgkmcnt(0)
	v_readfirstlane_b32 s1, v6
	v_cmp_gt_i32_e64 s[4:5], s0, v2
	v_readfirstlane_b32 s20, v5
	s_and_b64 s[4:5], s[10:11], s[4:5]
	v_mov_b32_e32 v10, v0
	v_mov_b32_e32 v11, v0
	v_mov_b64_e32 v[4:5], v[8:9]
	v_readfirstlane_b32 s27, v1
	s_and_b64 s[6:7], s[4:5], vcc
	v_mov_b64_e32 v[6:7], v[10:11]
	s_and_saveexec_b64 s[4:5], s[6:7]
	s_cbranch_execz .LBB0_549
	v_ashrrev_i32_e32 v3, 31, v2
	v_lshlrev_b64 v[2:3], 9, v[2:3]
	v_lshl_add_u64 v[2:3], v[40:41], 0, v[2:3]
	global_load_dwordx4 v[4:7], v[2:3], off
